# guard loads of the w_o and down phases issued ahead of the row-exchange polls (one round trip off each fused epilogue)
# speedup vs baseline: 1.0153x; 1.0052x over previous
.LBB0_814:
	s_or_b64 exec, exec, s[8:9]
	s_movk_i32 s1, 0x100
	v_cmp_gt_i32_e64 s[8:9], s1, v178
	s_movk_i32 s1, 0xff
	v_cmp_lt_i32_e32 vcc, s1, v178
	s_waitcnt vmcnt(0) lgkmcnt(0)
	s_barrier
	s_and_saveexec_b64 s[12:13], vcc
	s_xor_b64 s[12:13], exec, s[12:13]
	s_lshl_b32 s1, s0, 8
	s_or_saveexec_b64 s[12:13], s[12:13]
	v_mov_b32_e32 v181, s1
	v_add_u32_e32 v136, 0, v149
	s_xor_b64 exec, exec, s[12:13]
	s_cbranch_execz .LBB0_850
	ds_read_b128 v[128:131], v136
	s_lshl_b32 s29, s0, 8
	v_add_u32_e32 v132, s29, v178
	v_ashrrev_i32_e32 v133, 31, v132
	v_readlane_b32 s40, v252, 0
	s_waitcnt lgkmcnt(0)
	v_mov_b32_e32 v134, v129
	v_mov_b32_e32 v135, v130
	v_mov_b32_e32 v129, v131
	v_pk_add_f32 v[128:129], v[134:135], v[128:129]
	v_readlane_b32 s46, v252, 6
	v_pk_add_f32 v[130:131], v[128:129], v[128:129] op_sel:[0,1] op_sel_hi:[1,0]
	v_lshlrev_b64 v[128:129], 5, v[132:133]
	v_readlane_b32 s47, v252, 7
	s_mov_b64 s[0:1], 0xe420000
	s_ashr_i32 s11, s10, 31
	v_lshl_add_u64 v[128:129], s[46:47], 0, v[128:129]
	v_lshl_add_u64 v[128:129], v[128:129], 0, s[0:1]
	v_lshl_add_u64 v[132:133], s[10:11], 3, v[128:129]
	v_mov_b32_e32 v131, 1
	global_store_dwordx2 v[132:133], v[130:131], off sc1
	v_readlane_b32 s60, v252, 11
	v_readlane_b32 s61, v252, 12
	v_mov_b32_e32 v160, 0
	s_add_u32 s60, s60, 0x10000
	s_addc_u32 s61, s61, 0
	global_load_dword v161, v160, s[60:61] sc1
	v_mov_b32_e32 v133, 0
	s_mov_b64 s[0:1], 0
	s_mov_b64 s[14:15], 0xffffffff
	s_mov_b32 s11, 0x400001
	v_readlane_b32 s41, v252, 1
	v_readlane_b32 s42, v252, 2
	v_readlane_b32 s43, v252, 3
	v_readlane_b32 s44, v252, 4
	v_readlane_b32 s45, v252, 5
	s_branch .LBB0_820

.LBB0_849:
	s_or_b64 exec, exec, s[0:1]
	v_add_f32_e32 v128, 0, v132
	v_add_f32_e32 v128, v128, v133
	v_add_f32_e32 v128, v128, v134
	v_add_f32_e32 v128, v128, v138
	v_mov_b32_e32 v129, 0x358637bd
	v_fmac_f32_e32 v129, 0x3a800000, v128
	s_mov_b32 s0, 0xf800000
	v_mul_f32_e32 v128, 0x4f800000, v129
	v_cmp_gt_f32_e32 vcc, s0, v129
	v_mov_b32_e32 v181, s29
	s_nop 0
	v_cndmask_b32_e32 v128, v129, v128, vcc
	v_sqrt_f32_e32 v129, v128
	s_nop 0
	v_add_u32_e32 v130, -1, v129
	v_fma_f32 v131, -v130, v129, v128
	v_cmp_ge_f32_e64 s[0:1], 0, v131
	v_add_u32_e32 v131, 1, v129
	s_nop 0
	v_cndmask_b32_e64 v130, v129, v130, s[0:1]
	v_fma_f32 v129, -v131, v129, v128
	v_cmp_lt_f32_e64 s[0:1], 0, v129
	s_nop 1
	v_cndmask_b32_e64 v129, v130, v131, s[0:1]
	v_mul_f32_e32 v130, 0x37800000, v129
	v_cndmask_b32_e32 v129, v129, v130, vcc
	v_mov_b32_e32 v130, 0x260
	v_cmp_class_f32_e32 vcc, v128, v130
	s_nop 1
	v_cndmask_b32_e32 v128, v129, v128, vcc
	v_div_scale_f32 v129, s[0:1], v128, v128, 1.0
	v_rcp_f32_e32 v130, v129
	s_nop 0
	v_fma_f32 v131, -v129, v130, 1.0
	v_fmac_f32_e32 v130, v131, v130
	v_div_scale_f32 v131, vcc, 1.0, v128, 1.0
	v_mul_f32_e32 v132, v131, v130
	v_fma_f32 v133, -v129, v132, v131
	v_fmac_f32_e32 v132, v133, v130
	v_fma_f32 v129, -v129, v132, v131
	v_div_fmas_f32 v129, v129, v130, v132
	v_div_fixup_f32 v130, v129, v128, 1.0
	v_mad_u64_u32 v[128:129], s[0:1], v178, -12, v[136:137]
	ds_write_b32 v128, v130 offset:8192
	s_mov_b32 s16, 0
.Lgd4_spin:
	s_waitcnt vmcnt(0)
	v_cmp_le_u32_e32 vcc, s86, v161
	s_cbranch_vccnz .Lgd4_ok
	s_add_i32 s16, s16, 1
	s_cmp_lt_u32 s16, 0x400000
	s_cbranch_scc0 .Lgd4_ok
	s_sleep 1
	global_load_dword v161, v160, s[60:61] sc1
	s_branch .Lgd4_spin

.LBB0_1181:
	s_or_b64 exec, exec, s[0:1]
	s_movk_i32 s0, 0xff
	v_cmp_lt_i32_e32 vcc, s0, v148
	s_waitcnt vmcnt(0) lgkmcnt(0)
	s_barrier
	s_and_saveexec_b64 s[0:1], vcc
	s_xor_b64 s[0:1], exec, s[0:1]
	s_lshl_b32 s11, s12, 8
	s_or_saveexec_b64 s[6:7], s[0:1]
	v_mov_b32_e32 v128, s11
	s_xor_b64 exec, exec, s[6:7]
	s_cbranch_execz .LBB0_1217
	v_add_u32_e32 v128, 0, v151
	ds_read_b128 v[130:133], v128
	s_lshl_b32 s20, s12, 8
	v_add_u32_e32 v134, s20, v148
	v_ashrrev_i32_e32 v135, 31, v134
	v_readlane_b32 s12, v252, 0
	s_waitcnt lgkmcnt(0)
	v_mov_b32_e32 v136, v131
	v_mov_b32_e32 v137, v132
	v_mov_b32_e32 v131, v133
	v_pk_add_f32 v[130:131], v[136:137], v[130:131]
	v_readlane_b32 s18, v252, 6
	v_pk_add_f32 v[132:133], v[130:131], v[130:131] op_sel:[0,1] op_sel_hi:[1,0]
	v_lshlrev_b64 v[130:131], 5, v[134:135]
	v_readlane_b32 s19, v252, 7
	s_mov_b64 s[0:1], 0xe3a0000
	s_ashr_i32 s11, s10, 31
	v_lshl_add_u64 v[130:131], s[18:19], 0, v[130:131]
	v_lshl_add_u64 v[130:131], v[130:131], 0, s[0:1]
	v_readlane_b32 s13, v252, 1
	v_lshl_add_u64 v[134:135], s[10:11], 3, v[130:131]
	v_mov_b32_e32 v133, 1
	global_store_dwordx2 v[134:135], v[132:133], off sc1
	v_readlane_b32 s60, v252, 11
	v_readlane_b32 s61, v252, 12
	v_mov_b32_e32 v160, 0
	s_add_u32 s60, s60, 0x11000
	s_addc_u32 s61, s61, 0
	global_load_dword v161, v160, s[60:61] sc1
	v_mov_b32_e32 v134, 0
	s_mov_b64 s[0:1], 0
	s_mov_b64 s[12:13], 0xffffffff
	s_mov_b32 s11, 0x400001
	v_readlane_b32 s14, v252, 2
	v_readlane_b32 s15, v252, 3
	v_readlane_b32 s16, v252, 4
	v_readlane_b32 s17, v252, 5
	s_branch .LBB0_1187

.LBB0_1216:
	s_or_b64 exec, exec, s[0:1]
	s_mov_b32 s16, 0
